# P6 (out GEMM) slab-1 tail round K-split two ways with partial exchange; each workgroup runs half the epilogue on its own 128 rows (P9 tail likewise)
# speedup vs baseline: 1.0109x; 1.0076x over previous
;     __device__ __forceinline__ bool next(int i, Unit& u) const {
;         const int r = i / np; u.part = i - r * np;
;         long L = (long)r * G + c;
;         if (L >= split_from) { const long Ls = L - split_from; if (Ls >= 2L * (nwg - split_from)) return false; L = split_from + (Ls >> 1); u.part = 1 + (int)(Ls & 1); }
;         if (L >= nwg) return false;
.LBB0_778:
	s_add_i32 s53, s53, 1
	v_readlane_b32 s4, v253, 53
	v_readlane_b32 s20, v252, 0
	s_mul_i32 s4, s53, s4
	v_readlane_b32 s21, v252, 1
	s_mul_hi_u32 s5, s53, s20
	s_add_i32 s5, s5, s4
	s_mul_i32 s4, s53, s20
	v_readlane_b32 s20, v254, 38
	v_readlane_b32 s21, v254, 39
	s_add_u32 s20, s4, s20
	s_addc_u32 s21, s5, s21
	s_mov_b32 s101, 0
	s_cmp_lt_u32 s20, 0x100
	s_cbranch_scc1 .Lks6_ns
	s_cmp_le_u32 s10, 0x100
	s_cbranch_scc1 .Lks6_ns
	s_sub_i32 s14, s20, 0x100
	s_and_b32 s101, s14, 1
	s_add_i32 s101, s101, 1
	s_lshr_b32 s15, s14, 1
	s_add_i32 s20, s15, 0x100
	s_sub_i32 s15, s10, 0x100
	s_lshl_b32 s15, s15, 1
	s_cmp_lt_u32 s14, s15
	s_cselect_b32 s20, s20, 0x7fff

;     __device__ __forceinline__ const char* Ap(int part) const { return (const char*)A0 + (long)(part == 1) * ((const char*)A1 - (const char*)A0) + (long)(part == 2) * ((const char*)A2 - (const char*)A0); }
;     __device__ __forceinline__ const char* Bp(int part) const { return (const char*)B0 + (long)(part == 1) * ((const char*)B1 - (const char*)B0) + (long)(part == 2) * ((const char*)B2 - (const char*)B0); }
; #define PG8_STAGE(bufoff, gbase, voff) do { _Pragma("unroll") for (int _i = 0; _i < 2; ++_i) \
;         __builtin_amdgcn_global_load_lds((const unsigned*)((const char*)(gbase) + (voff)[_i]), (LAS unsigned*)(lds + (bufoff) + ldsw + _i * 8192), 16, 0, 0); } while (0)
; #define PG8_BAR __builtin_amdgcn_s_barrier()
; template <class Epi, bool GS = false>
; __device__ __forceinline__ void gemm_phase(LAS unsigned char* lds, const Gemm g, const StaticOrder& S, const Epi& E, const int tid) {
;     ...
;     const char* cA = g.Ap(cur.part) + (size_t)cur.pm * tstepA; const char* cB = g.Bp(cur.part) + (size_t)cur.pn * tstepB;
;     PG8_STAGE(PG8_SB(0, 0), cB, voffB); PG8_STAGE(PG8_SB(0, 1), cB + hstepB, voffB); PG8_STAGE(PG8_SA(0, 0), cA, voffA); PG8_STAGE(PG8_SA(0, 1), cA + hstepA, voffA);
;     if (wr == 1) PG8_BAR;
;     PG8_WAIT_V(2); PG8_BAR;
;     PG8_STAGE(PG8_SB(1, 0), cB + kstep, voffB); PG8_STAGE(PG8_SA(1, 0), cA + kstep, voffA); PG8_STAGE(PG8_SB(1, 1), cB + hstepB + kstep, voffB);
;     PG8_WAIT_V(6); PG8_BAR;
;     for (;;) {
;         const bool has_next = S.next(ui + 1, nxt);
;         const char* nA = has_next ? g.Ap(nxt.part) + (size_t)nxt.pm * tstepA : cA; const char* nB = has_next ? g.Bp(nxt.part) + (size_t)nxt.pn * tstepB : cB;
;         const int nt = g.Kp(cur.part) / BK;
;         const int seg = (GS && cur.part == 0) ? 8 : nt;
;         for (int tg = 0; tg < nt; tg += seg) {
;         for (int t = tg; t < tg + seg; t += 2) {
;             const bool last = (t == nt - 2);
;             const char* a1 = cA + (size_t)(t + 1) * kstep;
;             const char* a2 = last ? nA : cA + (size_t)(t + 2) * kstep; const char* b2 = last ? nB : cB + (size_t)(t + 2) * kstep;
;     ...
; #pragma unroll
;         for (int a = 0; a < 2; ++a)
; #pragma unroll
;             for (int b = 0; b < 2; ++b)
; #pragma unroll
;                 for (int m = 0; m < 4; ++m)
; #pragma unroll
;                     for (int n = 0; n < 2; ++n) acc[a][b][m][n] = (f32x4){0.f, 0.f, 0.f, 0.f};
.LBB0_780:
	s_ashr_i32 s17, s16, 31
	s_lshl_b64 s[20:21], s[16:17], 19
	s_add_u32 s20, s12, s20
	s_addc_u32 s21, s13, s21
	s_cmp_eq_u32 s101, 2
	s_cbranch_scc0 .Lks6_a
	s_add_u32 s20, s20, 0x400
	s_addc_u32 s21, s21, 0
.Lks6_a:
	s_and_b64 s[22:23], s[4:5], exec
	s_cselect_b32 s17, s21, s43
	s_cselect_b32 s39, s20, s42
	s_ashr_i32 s15, s14, 31
	s_lshl_b64 s[22:23], s[14:15], 19
	v_readlane_b32 s15, v255, 21
	s_add_u32 s22, s15, s22
	v_readlane_b32 s15, v255, 23
	s_addc_u32 s23, s15, s23
	s_cmp_eq_u32 s101, 2
	s_cbranch_scc0 .Lks6_b
	s_add_u32 s22, s22, 0x400
	s_addc_u32 s23, s23, 0
.Lks6_b:
	s_and_b64 s[46:47], s[4:5], exec
	s_cselect_b32 s15, s23, s45
	s_cselect_b32 s54, s22, s44
	s_add_u32 s42, s42, 0x40080
	s_addc_u32 s43, s43, 0
	s_add_u32 s55, s44, 0x100
	v_mov_b32_e32 v2, 0
	s_addc_u32 s56, s45, 0
	s_mov_b32 s57, -2
	s_cmp_eq_u32 s100, 0
	s_cselect_b32 s57, s57, 6
	v_mov_b32_e32 v3, v2
	v_mov_b32_e32 v4, v2
	v_mov_b32_e32 v5, v2
	v_mov_b32_e32 v6, v2
	v_mov_b32_e32 v7, v2
	v_mov_b32_e32 v8, v2
	v_mov_b32_e32 v9, v2
	v_mov_b32_e32 v18, v2
	v_mov_b32_e32 v19, v2
	v_mov_b32_e32 v20, v2
	v_mov_b32_e32 v21, v2
	v_mov_b32_e32 v22, v2
	v_mov_b32_e32 v23, v2
	v_mov_b32_e32 v24, v2
	v_mov_b32_e32 v25, v2
	v_mov_b32_e32 v34, v2
	v_mov_b32_e32 v35, v2
	v_mov_b32_e32 v36, v2
	v_mov_b32_e32 v37, v2
	v_mov_b32_e32 v38, v2
	v_mov_b32_e32 v39, v2
	v_mov_b32_e32 v40, v2
	v_mov_b32_e32 v41, v2
	s_waitcnt vmcnt(0)
	v_mov_b32_e32 v50, v2
	v_mov_b32_e32 v51, v2
	v_mov_b32_e32 v52, v2
	v_mov_b32_e32 v53, v2
	v_mov_b32_e32 v54, v2
	v_mov_b32_e32 v55, v2
	v_mov_b32_e32 v56, v2
	v_mov_b32_e32 v57, v2
	v_mov_b32_e32 v10, v2
	v_mov_b32_e32 v11, v2
	v_mov_b32_e32 v12, v2
	v_mov_b32_e32 v13, v2
	v_mov_b32_e32 v14, v2
	v_mov_b32_e32 v15, v2
	v_mov_b32_e32 v16, v2
	v_mov_b32_e32 v17, v2
	v_mov_b32_e32 v26, v2
	v_mov_b32_e32 v27, v2
	v_mov_b32_e32 v28, v2
	v_mov_b32_e32 v29, v2
	v_mov_b32_e32 v30, v2
	v_mov_b32_e32 v31, v2
	v_mov_b32_e32 v32, v2
	v_mov_b32_e32 v33, v2
	v_mov_b32_e32 v42, v2
	v_mov_b32_e32 v43, v2
	v_mov_b32_e32 v44, v2
	v_mov_b32_e32 v45, v2
	v_mov_b32_e32 v46, v2
	v_mov_b32_e32 v47, v2
	v_mov_b32_e32 v48, v2
	v_mov_b32_e32 v49, v2
	v_mov_b32_e32 v58, v2
	v_mov_b32_e32 v59, v2
	v_mov_b32_e32 v60, v2
	v_mov_b32_e32 v61, v2
	v_mov_b32_e32 v62, v2
	v_mov_b32_e32 v63, v2
	v_mov_b32_e32 v64, v2
	v_mov_b32_e32 v65, v2
	v_mov_b32_e32 v66, v2
	v_mov_b32_e32 v67, v2
	v_mov_b32_e32 v68, v2
	v_mov_b32_e32 v69, v2
	v_mov_b32_e32 v70, v2
	v_mov_b32_e32 v71, v2
	v_mov_b32_e32 v72, v2
	v_mov_b32_e32 v73, v2
	v_mov_b32_e32 v74, v2
	v_mov_b32_e32 v75, v2
	v_mov_b32_e32 v76, v2
	v_mov_b32_e32 v77, v2
	v_mov_b32_e32 v86, v2
	v_mov_b32_e32 v87, v2
	v_mov_b32_e32 v88, v2
	v_mov_b32_e32 v89, v2
	v_mov_b32_e32 v98, v2
	v_mov_b32_e32 v99, v2
	v_mov_b32_e32 v100, v2
	v_mov_b32_e32 v101, v2
	v_mov_b32_e32 v102, v2
	v_mov_b32_e32 v103, v2
	v_mov_b32_e32 v104, v2
	v_mov_b32_e32 v105, v2
	v_mov_b32_e32 v114, v2
	v_mov_b32_e32 v115, v2
	v_mov_b32_e32 v116, v2
	v_mov_b32_e32 v117, v2
	v_mov_b32_e32 v118, v2
	v_mov_b32_e32 v119, v2
	v_mov_b32_e32 v120, v2
	v_mov_b32_e32 v121, v2
	v_mov_b32_e32 v78, v2
	v_mov_b32_e32 v79, v2
	v_mov_b32_e32 v80, v2
	v_mov_b32_e32 v81, v2
	v_mov_b32_e32 v82, v2
	v_mov_b32_e32 v83, v2
	v_mov_b32_e32 v84, v2
	v_mov_b32_e32 v85, v2
	v_mov_b32_e32 v90, v2
	v_mov_b32_e32 v91, v2
	v_mov_b32_e32 v92, v2
	v_mov_b32_e32 v93, v2
	v_mov_b32_e32 v94, v2
	v_mov_b32_e32 v95, v2
	v_mov_b32_e32 v96, v2
	v_mov_b32_e32 v97, v2
	v_mov_b32_e32 v106, v2
	v_mov_b32_e32 v107, v2
	v_mov_b32_e32 v108, v2
	v_mov_b32_e32 v109, v2
	v_mov_b32_e32 v110, v2
	v_mov_b32_e32 v111, v2
	v_mov_b32_e32 v112, v2
	v_mov_b32_e32 v113, v2
	v_mov_b32_e32 v122, v2
	v_mov_b32_e32 v123, v2
	v_mov_b32_e32 v124, v2
	v_mov_b32_e32 v125, v2
	v_mov_b32_e32 v126, v2
	v_mov_b32_e32 v127, v2
	v_mov_b32_e32 v128, v2
	v_mov_b32_e32 v129, v2

; #define PG8_BAR __builtin_amdgcn_s_barrier()
; template <class Epi, bool GS = false>
; __device__ __forceinline__ void gemm_phase(LAS unsigned char* lds, const Gemm g, const StaticOrder& S, const Epi& E, const int tid) {
;     ...
;         }
;         if (wr == 0) PG8_BAR;
;         E(acc, cur, wr, wc, fr, fq);
.LBB0_784:
	s_cmp_eq_u32 s100, 0
	s_cbranch_scc1 .Lks6_done
	v_readlane_b32 s28, v252, 2
	s_lshr_b32 s28, s28, 9
	s_lshl_b32 s29, s28, 17
	s_xor_b32 s42, s28, 1
	s_lshl_b32 s43, s42, 17
	v_lshlrev_b32_e32 v130, 4, v166
	v_add_u32_e32 v131, s43, v130
	v_add_u32_e32 v130, s29, v130
	s_cmp_eq_u32 s100, 1
	s_cbranch_scc0 .Lks6_send1
	global_store_dwordx4 v130, v[2:5], s[18:19] sc0 sc1
	v_add_u32_e32 v130, 0x2000, v130
	global_store_dwordx4 v130, v[6:9], s[18:19] sc0 sc1
	v_add_u32_e32 v130, 0x2000, v130
	global_store_dwordx4 v130, v[10:13], s[18:19] sc0 sc1
	v_add_u32_e32 v130, 0x2000, v130
	global_store_dwordx4 v130, v[14:17], s[18:19] sc0 sc1
	v_add_u32_e32 v130, 0x2000, v130
	global_store_dwordx4 v130, v[18:21], s[18:19] sc0 sc1
	v_add_u32_e32 v130, 0x2000, v130
	global_store_dwordx4 v130, v[22:25], s[18:19] sc0 sc1
	v_add_u32_e32 v130, 0x2000, v130
	global_store_dwordx4 v130, v[26:29], s[18:19] sc0 sc1
	v_add_u32_e32 v130, 0x2000, v130
	global_store_dwordx4 v130, v[30:33], s[18:19] sc0 sc1
	v_add_u32_e32 v130, 0x2000, v130
	global_store_dwordx4 v130, v[34:37], s[18:19] sc0 sc1
	v_add_u32_e32 v130, 0x2000, v130
	global_store_dwordx4 v130, v[38:41], s[18:19] sc0 sc1
	v_add_u32_e32 v130, 0x2000, v130
	global_store_dwordx4 v130, v[42:45], s[18:19] sc0 sc1
	v_add_u32_e32 v130, 0x2000, v130
	global_store_dwordx4 v130, v[46:49], s[18:19] sc0 sc1
	v_add_u32_e32 v130, 0x2000, v130
	global_store_dwordx4 v130, v[50:53], s[18:19] sc0 sc1
	v_add_u32_e32 v130, 0x2000, v130
	global_store_dwordx4 v130, v[54:57], s[18:19] sc0 sc1
	v_add_u32_e32 v130, 0x2000, v130
	global_store_dwordx4 v130, v[58:61], s[18:19] sc0 sc1
	v_add_u32_e32 v130, 0x2000, v130
	global_store_dwordx4 v130, v[62:65], s[18:19] sc0 sc1
	v_add_u32_e32 v130, 0x2000, v130
	s_branch .Lks6_sent
.Lks6_send1:
	global_store_dwordx4 v130, v[66:69], s[18:19] sc0 sc1
	v_add_u32_e32 v130, 0x2000, v130
	global_store_dwordx4 v130, v[70:73], s[18:19] sc0 sc1
	v_add_u32_e32 v130, 0x2000, v130
	global_store_dwordx4 v130, v[74:77], s[18:19] sc0 sc1
	v_add_u32_e32 v130, 0x2000, v130
	global_store_dwordx4 v130, v[78:81], s[18:19] sc0 sc1
	v_add_u32_e32 v130, 0x2000, v130
	global_store_dwordx4 v130, v[82:85], s[18:19] sc0 sc1
	v_add_u32_e32 v130, 0x2000, v130
	global_store_dwordx4 v130, v[86:89], s[18:19] sc0 sc1
	v_add_u32_e32 v130, 0x2000, v130
	global_store_dwordx4 v130, v[90:93], s[18:19] sc0 sc1
	v_add_u32_e32 v130, 0x2000, v130
	global_store_dwordx4 v130, v[94:97], s[18:19] sc0 sc1
	v_add_u32_e32 v130, 0x2000, v130
	global_store_dwordx4 v130, v[98:101], s[18:19] sc0 sc1
	v_add_u32_e32 v130, 0x2000, v130
	global_store_dwordx4 v130, v[102:105], s[18:19] sc0 sc1
	v_add_u32_e32 v130, 0x2000, v130
	global_store_dwordx4 v130, v[106:109], s[18:19] sc0 sc1
	v_add_u32_e32 v130, 0x2000, v130
	global_store_dwordx4 v130, v[110:113], s[18:19] sc0 sc1
	v_add_u32_e32 v130, 0x2000, v130
	global_store_dwordx4 v130, v[114:117], s[18:19] sc0 sc1
	v_add_u32_e32 v130, 0x2000, v130
	global_store_dwordx4 v130, v[118:121], s[18:19] sc0 sc1
	v_add_u32_e32 v130, 0x2000, v130
	global_store_dwordx4 v130, v[122:125], s[18:19] sc0 sc1
	v_add_u32_e32 v130, 0x2000, v130
	global_store_dwordx4 v130, v[126:129], s[18:19] sc0 sc1
	v_add_u32_e32 v130, 0x2000, v130
.Lks6_sent:
	s_waitcnt vmcnt(0)
	s_barrier
	v_readfirstlane_b32 s44, v166
	s_nop 0
	s_cmp_lt_u32 s44, 64
	s_cbranch_scc0 .Lks6_wait
	s_lshl_b32 s45, s42, 2
	s_addk_i32 s45, 0x3600
	v_mov_b32_e32 v132, s45
	v_mov_b32_e32 v133, 1
	s_lshl_b32 s45, s28, 2
	s_addk_i32 s45, 0x3600
	v_mov_b32_e32 v134, s45
	s_add_u32 s54, s26, 0x1d780000
	s_addc_u32 s55, s27, 0
	global_store_dword v132, v133, s[54:55] sc0 sc1
	s_mov_b32 s47, 0
.Lks6_poll:
	global_load_dword v135, v134, s[54:55] sc0 sc1
	s_waitcnt vmcnt(0)
	v_readfirstlane_b32 s46, v135
	s_add_i32 s47, s47, 1
	s_cmp_eq_u32 s46, 1
	s_cbranch_scc1 .Lks6_got
	s_sleep 1
	s_cmp_lt_u32 s47, 0x8000
	s_cbranch_scc1 .Lks6_poll

; #define PG8_BAR __builtin_amdgcn_s_barrier()
; template <class Epi, bool GS = false>
; __device__ __forceinline__ void gemm_phase(LAS unsigned char* lds, const Gemm g, const StaticOrder& S, const Epi& E, const int tid) {
;     ...
;         }
;         if (wr == 0) PG8_BAR;
;         E(acc, cur, wr, wc, fr, fq);
.Lks6_wait:
	s_barrier
	s_cmp_eq_u32 s100, 1
	s_cbranch_scc0 .Lks6_recv1
	global_load_dwordx4 v[2:5], v131, s[18:19] sc0 sc1
	v_add_u32_e32 v131, 0x2000, v131
	global_load_dwordx4 v[6:9], v131, s[18:19] sc0 sc1
	v_add_u32_e32 v131, 0x2000, v131
	global_load_dwordx4 v[10:13], v131, s[18:19] sc0 sc1
	v_add_u32_e32 v131, 0x2000, v131
	global_load_dwordx4 v[14:17], v131, s[18:19] sc0 sc1
	v_add_u32_e32 v131, 0x2000, v131
	global_load_dwordx4 v[18:21], v131, s[18:19] sc0 sc1
	v_add_u32_e32 v131, 0x2000, v131
	global_load_dwordx4 v[22:25], v131, s[18:19] sc0 sc1
	v_add_u32_e32 v131, 0x2000, v131
	global_load_dwordx4 v[26:29], v131, s[18:19] sc0 sc1
	v_add_u32_e32 v131, 0x2000, v131
	global_load_dwordx4 v[30:33], v131, s[18:19] sc0 sc1
	v_add_u32_e32 v131, 0x2000, v131
	global_load_dwordx4 v[34:37], v131, s[18:19] sc0 sc1
	v_add_u32_e32 v131, 0x2000, v131
	global_load_dwordx4 v[38:41], v131, s[18:19] sc0 sc1
	v_add_u32_e32 v131, 0x2000, v131
	global_load_dwordx4 v[42:45], v131, s[18:19] sc0 sc1
	v_add_u32_e32 v131, 0x2000, v131
	global_load_dwordx4 v[46:49], v131, s[18:19] sc0 sc1
	v_add_u32_e32 v131, 0x2000, v131
	global_load_dwordx4 v[50:53], v131, s[18:19] sc0 sc1
	v_add_u32_e32 v131, 0x2000, v131
	global_load_dwordx4 v[54:57], v131, s[18:19] sc0 sc1
	v_add_u32_e32 v131, 0x2000, v131
	global_load_dwordx4 v[58:61], v131, s[18:19] sc0 sc1
	v_add_u32_e32 v131, 0x2000, v131
	global_load_dwordx4 v[62:65], v131, s[18:19] sc0 sc1
	v_add_u32_e32 v131, 0x2000, v131
	s_waitcnt vmcnt(15)
	v_pk_add_f32 v[66:67], v[66:67], v[2:3]
	v_pk_add_f32 v[68:69], v[68:69], v[4:5]
	s_waitcnt vmcnt(14)
	v_pk_add_f32 v[70:71], v[70:71], v[6:7]
	v_pk_add_f32 v[72:73], v[72:73], v[8:9]
	s_waitcnt vmcnt(13)
	v_pk_add_f32 v[74:75], v[74:75], v[10:11]
	v_pk_add_f32 v[76:77], v[76:77], v[12:13]
	s_waitcnt vmcnt(12)
	v_pk_add_f32 v[78:79], v[78:79], v[14:15]
	v_pk_add_f32 v[80:81], v[80:81], v[16:17]
	s_waitcnt vmcnt(11)
	v_pk_add_f32 v[82:83], v[82:83], v[18:19]
	v_pk_add_f32 v[84:85], v[84:85], v[20:21]
	s_waitcnt vmcnt(10)
	v_pk_add_f32 v[86:87], v[86:87], v[22:23]
	v_pk_add_f32 v[88:89], v[88:89], v[24:25]
	s_waitcnt vmcnt(9)
	v_pk_add_f32 v[90:91], v[90:91], v[26:27]
	v_pk_add_f32 v[92:93], v[92:93], v[28:29]
	s_waitcnt vmcnt(8)
	v_pk_add_f32 v[94:95], v[94:95], v[30:31]
	v_pk_add_f32 v[96:97], v[96:97], v[32:33]
	s_waitcnt vmcnt(7)
	v_pk_add_f32 v[98:99], v[98:99], v[34:35]
	v_pk_add_f32 v[100:101], v[100:101], v[36:37]
	s_waitcnt vmcnt(6)
	v_pk_add_f32 v[102:103], v[102:103], v[38:39]
	v_pk_add_f32 v[104:105], v[104:105], v[40:41]
	s_waitcnt vmcnt(5)
	v_pk_add_f32 v[106:107], v[106:107], v[42:43]
	v_pk_add_f32 v[108:109], v[108:109], v[44:45]
	s_waitcnt vmcnt(4)
	v_pk_add_f32 v[110:111], v[110:111], v[46:47]
	v_pk_add_f32 v[112:113], v[112:113], v[48:49]
	s_waitcnt vmcnt(3)
	v_pk_add_f32 v[114:115], v[114:115], v[50:51]
	v_pk_add_f32 v[116:117], v[116:117], v[52:53]
	s_waitcnt vmcnt(2)
	v_pk_add_f32 v[118:119], v[118:119], v[54:55]
	v_pk_add_f32 v[120:121], v[120:121], v[56:57]
	s_waitcnt vmcnt(1)
	v_pk_add_f32 v[122:123], v[122:123], v[58:59]
	v_pk_add_f32 v[124:125], v[124:125], v[60:61]
	s_waitcnt vmcnt(0)
	v_pk_add_f32 v[126:127], v[126:127], v[62:63]
	v_pk_add_f32 v[128:129], v[128:129], v[64:65]
	s_branch .Lks6_done
.Lks6_recv1:
	global_load_dwordx4 v[66:69], v131, s[18:19] sc0 sc1
	v_add_u32_e32 v131, 0x2000, v131
	global_load_dwordx4 v[70:73], v131, s[18:19] sc0 sc1
	v_add_u32_e32 v131, 0x2000, v131
	global_load_dwordx4 v[74:77], v131, s[18:19] sc0 sc1
	v_add_u32_e32 v131, 0x2000, v131
	global_load_dwordx4 v[78:81], v131, s[18:19] sc0 sc1
	v_add_u32_e32 v131, 0x2000, v131
	global_load_dwordx4 v[82:85], v131, s[18:19] sc0 sc1
	v_add_u32_e32 v131, 0x2000, v131
	global_load_dwordx4 v[86:89], v131, s[18:19] sc0 sc1
	v_add_u32_e32 v131, 0x2000, v131
	global_load_dwordx4 v[90:93], v131, s[18:19] sc0 sc1
	v_add_u32_e32 v131, 0x2000, v131
	global_load_dwordx4 v[94:97], v131, s[18:19] sc0 sc1
	v_add_u32_e32 v131, 0x2000, v131
	global_load_dwordx4 v[98:101], v131, s[18:19] sc0 sc1
	v_add_u32_e32 v131, 0x2000, v131
	global_load_dwordx4 v[102:105], v131, s[18:19] sc0 sc1
	v_add_u32_e32 v131, 0x2000, v131
	global_load_dwordx4 v[106:109], v131, s[18:19] sc0 sc1
	v_add_u32_e32 v131, 0x2000, v131
	global_load_dwordx4 v[110:113], v131, s[18:19] sc0 sc1
	v_add_u32_e32 v131, 0x2000, v131
	global_load_dwordx4 v[114:117], v131, s[18:19] sc0 sc1
	v_add_u32_e32 v131, 0x2000, v131
	global_load_dwordx4 v[118:121], v131, s[18:19] sc0 sc1
	v_add_u32_e32 v131, 0x2000, v131
	global_load_dwordx4 v[122:125], v131, s[18:19] sc0 sc1
	v_add_u32_e32 v131, 0x2000, v131
	global_load_dwordx4 v[126:129], v131, s[18:19] sc0 sc1
	v_add_u32_e32 v131, 0x2000, v131
	s_waitcnt vmcnt(15)
	v_pk_add_f32 v[2:3], v[2:3], v[66:67]
	v_pk_add_f32 v[4:5], v[4:5], v[68:69]
	s_waitcnt vmcnt(14)
	v_pk_add_f32 v[6:7], v[6:7], v[70:71]
	v_pk_add_f32 v[8:9], v[8:9], v[72:73]
	s_waitcnt vmcnt(13)
	v_pk_add_f32 v[10:11], v[10:11], v[74:75]
	v_pk_add_f32 v[12:13], v[12:13], v[76:77]
	s_waitcnt vmcnt(12)
	v_pk_add_f32 v[14:15], v[14:15], v[78:79]
	v_pk_add_f32 v[16:17], v[16:17], v[80:81]
	s_waitcnt vmcnt(11)
	v_pk_add_f32 v[18:19], v[18:19], v[82:83]
	v_pk_add_f32 v[20:21], v[20:21], v[84:85]
	s_waitcnt vmcnt(10)
	v_pk_add_f32 v[22:23], v[22:23], v[86:87]
	v_pk_add_f32 v[24:25], v[24:25], v[88:89]
	s_waitcnt vmcnt(9)
	v_pk_add_f32 v[26:27], v[26:27], v[90:91]
	v_pk_add_f32 v[28:29], v[28:29], v[92:93]
	s_waitcnt vmcnt(8)
	v_pk_add_f32 v[30:31], v[30:31], v[94:95]
	v_pk_add_f32 v[32:33], v[32:33], v[96:97]
	s_waitcnt vmcnt(7)
	v_pk_add_f32 v[34:35], v[34:35], v[98:99]
	v_pk_add_f32 v[36:37], v[36:37], v[100:101]
	s_waitcnt vmcnt(6)
;     __device__ __forceinline__ void operator()(const f32x4 (&acc)[2][2][4][2], const Unit& u, int wr, int wc, int fr, int fq) const {
;         const int col0 = u.pn * BM + wc * 32 + 4 * fq;
; #pragma unroll
;         for (int ai = 0; ai < 2; ++ai) {
;             const int grb = row_base + u.pm * BM + ai * HALF + wr * 64;
;             const int seq = grb < MP ? (grb >> 11) : NPB + ((grb - MP) >> 6);
;             const float* gp = gate + (size_t)seq * (6 * DM) + col0;
;             f32x4 gv[2][2];
; #pragma unroll
;             for (int bj = 0; bj < 2; ++bj)
; #pragma unroll
;                 for (int n = 0; n < 2; ++n) gv[bj][n] = *(const f32x4*)(gp + bj * HALF + n * 16);
;             if (u.part == 0) {
; #pragma unroll
;                 for (int mp = 0; mp < 2; ++mp) {
;                 f32x4 xv[2][2][2];
; #pragma unroll
;                 for (int mm = 0; mm < 2; ++mm) { const int gr = grb + (2 * mp + mm) * 16 + fr;
;                     const float* xr = (gr < MP ? xin_p + (size_t)gr * DM : xin_s + (size_t)(gr - MP) * DM) + col0;
; #pragma unroll
;                     for (int bj = 0; bj < 2; ++bj)
; #pragma unroll
;                         for (int n = 0; n < 2; ++n) xv[mm][bj][n] = *(const f32x4*)(xr + bj * HALF + n * 16); }
	v_pk_add_f32 v[38:39], v[38:39], v[102:103]
	v_pk_add_f32 v[40:41], v[40:41], v[104:105]
	s_waitcnt vmcnt(5)
	v_pk_add_f32 v[42:43], v[42:43], v[106:107]
	v_pk_add_f32 v[44:45], v[44:45], v[108:109]
	s_waitcnt vmcnt(4)
	v_pk_add_f32 v[46:47], v[46:47], v[110:111]
	v_pk_add_f32 v[48:49], v[48:49], v[112:113]
	s_waitcnt vmcnt(3)
	v_pk_add_f32 v[50:51], v[50:51], v[114:115]
	v_pk_add_f32 v[52:53], v[52:53], v[116:117]
	s_waitcnt vmcnt(2)
	v_pk_add_f32 v[54:55], v[54:55], v[118:119]
	v_pk_add_f32 v[56:57], v[56:57], v[120:121]
	s_waitcnt vmcnt(1)
	v_pk_add_f32 v[58:59], v[58:59], v[122:123]
	v_pk_add_f32 v[60:61], v[60:61], v[124:125]
	s_waitcnt vmcnt(0)
	v_pk_add_f32 v[62:63], v[62:63], v[126:127]
	v_pk_add_f32 v[64:65], v[64:65], v[128:129]
	v_mov_b64_e32 v[66:67], v[2:3]
	v_mov_b64_e32 v[68:69], v[4:5]
	v_mov_b64_e32 v[70:71], v[6:7]
	v_mov_b64_e32 v[72:73], v[8:9]
	v_mov_b64_e32 v[78:79], v[10:11]
	v_mov_b64_e32 v[80:81], v[12:13]
	v_mov_b64_e32 v[82:83], v[14:15]
	v_mov_b64_e32 v[84:85], v[16:17]
	v_mov_b64_e32 v[74:75], v[18:19]
	v_mov_b64_e32 v[76:77], v[20:21]
	v_mov_b64_e32 v[86:87], v[22:23]
	v_mov_b64_e32 v[88:89], v[24:25]
	v_mov_b64_e32 v[90:91], v[26:27]
	v_mov_b64_e32 v[92:93], v[28:29]
	v_mov_b64_e32 v[94:95], v[30:31]
	v_mov_b64_e32 v[96:97], v[32:33]
	v_mov_b64_e32 v[98:99], v[34:35]
	v_mov_b64_e32 v[100:101], v[36:37]
	v_mov_b64_e32 v[102:103], v[38:39]
	v_mov_b64_e32 v[104:105], v[40:41]
	v_mov_b64_e32 v[106:107], v[42:43]
	v_mov_b64_e32 v[108:109], v[44:45]
	v_mov_b64_e32 v[110:111], v[46:47]
	v_mov_b64_e32 v[112:113], v[48:49]
	v_mov_b64_e32 v[114:115], v[50:51]
	v_mov_b64_e32 v[116:117], v[52:53]
	v_mov_b64_e32 v[118:119], v[54:55]
	v_mov_b64_e32 v[120:121], v[56:57]
	v_mov_b64_e32 v[122:123], v[58:59]
	v_mov_b64_e32 v[124:125], v[60:61]
	v_mov_b64_e32 v[126:127], v[62:63]
	v_mov_b64_e32 v[128:129], v[64:65]
.Lks6_done:
	s_lshl_b32 s15, s38, 8
	s_add_i32 s17, s36, s15
	s_cmp_eq_u32 s100, 2
	s_cselect_b32 s39, 0x80, 0
	s_add_i32 s17, s17, s39
	s_add_i32 s39, s17, 0xffff8000
	s_lshr_b32 s39, s39, 6
	s_ashr_i32 s38, s17, 11
	s_add_i32 s39, s39, 16
	s_cmp_lt_i32 s17, 0x8000
	v_or_b32_e32 v182, s17, v169
	s_mov_b32 s17, 0x8000
	v_add_u32_e32 v0, 0xffff8000, v182
	v_cmp_gt_i32_e32 vcc, s17, v182
	s_cselect_b32 s38, s38, s39
	v_ashrrev_i32_e32 v183, 31, v182
	v_cndmask_b32_e32 v146, v0, v182, vcc
	v_mov_b32_e32 v0, s35
	v_mov_b32_e32 v148, s31
	v_lshl_or_b32 v130, s40, 8, v191
	s_mul_hi_i32 s39, s38, 0x6000
	s_mulk_i32 s38, 0x6000
	v_readlane_b32 s28, v255, 25
	v_cndmask_b32_e32 v147, 0, v183, vcc
	v_cndmask_b32_e32 v149, v0, v148, vcc
	v_mov_b32_e32 v0, s34
	v_mov_b32_e32 v148, s30
	v_ashrrev_i32_e32 v131, 31, v130
	s_add_u32 s38, s28, s38
	v_readlane_b32 s28, v255, 27
	v_cndmask_b32_e32 v148, v0, v148, vcc
	v_lshlrev_b64 v[146:147], 12, v[146:147]
	s_addc_u32 s39, s28, s39
	v_lshlrev_b64 v[180:181], 2, v[130:131]
	v_lshl_add_u64 v[146:147], v[148:149], 0, v[146:147]
	v_lshl_add_u64 v[130:131], s[38:39], 0, v[180:181]
	v_lshl_add_u64 v[146:147], v[146:147], 0, v[180:181]
	global_load_dwordx4 v[142:145], v[130:131], off
	global_load_dwordx4 v[138:141], v[130:131], off offset:64
	global_load_dwordx4 v[134:137], v[130:131], off offset:512
	s_nop 0
	global_load_dwordx4 v[130:133], v[130:131], off offset:576
	s_nop 0
	global_load_dwordx4 v[158:161], v[146:147], off
	global_load_dwordx4 v[154:157], v[146:147], off offset:64
	global_load_dwordx4 v[150:153], v[146:147], off offset:512
	s_nop 0
	global_load_dwordx4 v[146:149], v[146:147], off offset:576
	v_or_b32_e32 v186, 16, v182
	s_movk_i32 s17, 0x7fff
	v_cmp_lt_i32_e32 vcc, s17, v186
	s_and_saveexec_b64 s[38:39], vcc
	s_xor_b64 s[38:39], exec, s[38:39]
	v_add_u32_e32 v0, 0xffff8010, v182
	v_lshlrev_b64 v[170:171], 12, v[0:1]
	v_mov_b32_e32 v187, v1
	v_lshl_add_u64 v[188:189], s[34:35], 0, v[170:171]
	v_lshlrev_b64 v[184:185], 12, v[186:187]
	s_andn2_saveexec_b64 s[38:39], s[38:39]
	v_ashrrev_i32_e32 v187, 31, v186
	v_lshlrev_b64 v[184:185], 12, v[186:187]
	v_lshl_add_u64 v[188:189], s[30:31], 0, v[184:185]
	s_or_b64 exec, exec, s[38:39]
	v_lshl_add_u64 v[170:171], v[188:189], 0, v[180:181]
	global_load_dwordx4 v[186:189], v[170:171], off
	global_load_dwordx4 v[216:219], v[170:171], off offset:64
	global_load_dwordx4 v[220:223], v[170:171], off offset:512
	global_load_dwordx4 v[224:227], v[170:171], off offset:576
	v_lshlrev_b64 v[170:171], 12, v[182:183]
	s_waitcnt vmcnt(0)
;     __device__ __forceinline__ void operator()(const f32x4 (&acc)[2][2][4][2], const Unit& u, int wr, int wc, int fr, int fq) const {
;     ...
;                 for (int mm = 0; mm < 2; ++mm) { const int gr = grb + (2 * mp + mm) * 16 + fr;
;                     const float* xr = (gr < MP ? xin_p + (size_t)gr * DM : xin_s + (size_t)(gr - MP) * DM) + col0;
; #pragma unroll
;                     for (int bj = 0; bj < 2; ++bj)
; #pragma unroll
;                         for (int n = 0; n < 2; ++n) xv[mm][bj][n] = *(const f32x4*)(xr + bj * HALF + n * 16); }
; #pragma unroll
;                 for (int mm = 0; mm < 2; ++mm) { const int m = 2 * mp + mm; const int gr = grb + m * 16 + fr; float* orow = out + (size_t)gr * DM + col0;
; #pragma unroll
;                     for (int bj = 0; bj < 2; ++bj)
; #pragma unroll
;                         for (int n = 0; n < 2; ++n) *(f32x4*)(orow + bj * HALF + n * 16) = xv[mm][bj][n] + gv[bj][n] * acc[ai][bj][m][n]; }
	v_pk_fma_f32 v[148:149], v[116:117], v[132:133], v[148:149]
	v_or_b32_e32 v116, 32, v182
	s_mov_b32 s17, 0x8000
	v_pk_fma_f32 v[118:119], v[118:119], v[134:135], v[150:151]
	v_add_u32_e32 v0, 0xffff8020, v182
	v_lshl_add_u64 v[150:151], s[24:25], 0, v[170:171]
	v_ashrrev_i32_e32 v117, 31, v116
	v_cmp_gt_i32_e32 vcc, s17, v116
	v_pk_fma_f32 v[128:129], v[128:129], v[144:145], v[160:161]
	v_pk_fma_f32 v[126:127], v[126:127], v[142:143], v[158:159]
	v_pk_fma_f32 v[124:125], v[124:125], v[140:141], v[156:157]
	v_pk_fma_f32 v[122:123], v[122:123], v[138:139], v[154:155]
	v_pk_fma_f32 v[120:121], v[120:121], v[136:137], v[152:153]
	v_mov_b32_e32 v154, s35
	v_mov_b32_e32 v155, s31
	v_mov_b32_e32 v156, s34
	v_mov_b32_e32 v157, s30
	v_lshl_add_u64 v[150:151], v[150:151], 0, v[180:181]
	v_cndmask_b32_e32 v153, 0, v117, vcc
	v_cndmask_b32_e32 v152, v0, v116, vcc
	v_pk_fma_f32 v[146:147], v[114:115], v[130:131], v[146:147]
	v_lshl_add_u64 v[114:115], s[24:25], 0, v[184:185]
	v_cndmask_b32_e32 v155, v154, v155, vcc
	v_cndmask_b32_e32 v154, v156, v157, vcc
	global_store_dwordx4 v[150:151], v[126:129], off
	global_store_dwordx4 v[150:151], v[122:125], off offset:64
	global_store_dwordx4 v[150:151], v[118:121], off offset:512
	global_store_dwordx4 v[150:151], v[146:149], off offset:576
	v_lshl_add_u64 v[114:115], v[114:115], 0, v[180:181]
	v_lshlrev_b64 v[118:119], 12, v[152:153]
	v_lshl_add_u64 v[118:119], v[154:155], 0, v[118:119]
	v_lshl_add_u64 v[118:119], v[118:119], 0, v[180:181]
	s_movk_i32 s17, 0x7fff
	v_pk_fma_f32 v[112:113], v[112:113], v[144:145], v[188:189]
	v_pk_fma_f32 v[110:111], v[110:111], v[142:143], v[186:187]
	v_pk_fma_f32 v[108:109], v[108:109], v[140:141], v[218:219]
	v_pk_fma_f32 v[106:107], v[106:107], v[138:139], v[216:217]
	v_pk_fma_f32 v[104:105], v[104:105], v[136:137], v[222:223]
	v_pk_fma_f32 v[102:103], v[102:103], v[134:135], v[220:221]
	v_pk_fma_f32 v[100:101], v[100:101], v[132:133], v[226:227]
	v_pk_fma_f32 v[98:99], v[98:99], v[130:131], v[224:225]
	global_store_dwordx4 v[114:115], v[110:113], off
	global_store_dwordx4 v[114:115], v[106:109], off offset:64
	global_store_dwordx4 v[114:115], v[102:105], off offset:512
	global_store_dwordx4 v[114:115], v[98:101], off offset:576
	global_load_dwordx4 v[110:113], v[118:119], off
	s_nop 0
	global_load_dwordx4 v[106:109], v[118:119], off offset:64
	global_load_dwordx4 v[102:105], v[118:119], off offset:512
	global_load_dwordx4 v[98:101], v[118:119], off offset:576
	v_or_b32_e32 v118, 48, v182
	v_cmp_lt_i32_e32 vcc, s17, v118
	s_and_saveexec_b64 s[38:39], vcc
	s_xor_b64 s[38:39], exec, s[38:39]
	v_add_u32_e32 v0, 0xffff8030, v182
	v_lshlrev_b64 v[114:115], 12, v[0:1]
	v_mov_b32_e32 v119, v1
	v_lshl_add_u64 v[120:121], s[34:35], 0, v[114:115]
	v_lshlrev_b64 v[114:115], 12, v[118:119]
	s_andn2_saveexec_b64 s[38:39], s[38:39]
	v_ashrrev_i32_e32 v119, 31, v118
	v_lshlrev_b64 v[114:115], 12, v[118:119]
	v_lshl_add_u64 v[120:121], s[30:31], 0, v[114:115]
	s_or_b64 exec, exec, s[38:39]
	v_lshl_add_u64 v[146:147], v[120:121], 0, v[180:181]
	global_load_dwordx4 v[118:121], v[146:147], off
	global_load_dwordx4 v[122:125], v[146:147], off offset:64
	global_load_dwordx4 v[126:129], v[146:147], off offset:512
	s_nop 0
	global_load_dwordx4 v[146:149], v[146:147], off offset:576
	s_add_i32 s15, s52, s15
	s_add_i32 s38, s15, 0xffff8000
	v_lshlrev_b64 v[116:117], 12, v[116:117]
	s_lshr_b32 s38, s38, 6
	v_lshl_add_u64 v[116:117], s[24:25], 0, v[116:117]
	s_ashr_i32 s17, s15, 11
	s_add_i32 s38, s38, 16
	v_lshl_add_u64 v[116:117], v[116:117], 0, v[180:181]
	s_waitcnt vmcnt(4)
	v_pk_fma_f32 v[76:77], v[76:77], v[132:133], v[100:101]
	v_pk_fma_f32 v[74:75], v[74:75], v[130:131], v[98:99]
	s_cmp_lt_i32 s15, 0x8000
	v_or_b32_e32 v98, s15, v169
	s_mov_b32 s15, 0x8000
	v_pk_fma_f32 v[88:89], v[88:89], v[136:137], v[104:105]
	v_pk_fma_f32 v[86:87], v[86:87], v[134:135], v[102:103]
	global_store_dwordx4 v[116:117], v[74:77], off offset:576
	v_cmp_gt_i32_e32 vcc, s15, v98
	v_add_u32_e32 v0, 0xffff8000, v98
	v_lshl_add_u64 v[74:75], s[24:25], 0, v[114:115]
	global_store_dwordx4 v[116:117], v[86:89], off offset:512
	s_cselect_b32 s17, s17, s38
	v_ashrrev_i32_e32 v99, 31, v98
	v_lshl_add_u64 v[86:87], v[74:75], 0, v[180:181]
	s_mul_hi_i32 s39, s17, 0x6000
	s_mulk_i32 s17, 0x6000
	v_readlane_b32 s28, v255, 25
	v_pk_fma_f32 v[96:97], v[96:97], v[144:145], v[112:113]
	v_pk_fma_f32 v[94:95], v[94:95], v[142:143], v[110:111]
	v_pk_fma_f32 v[92:93], v[92:93], v[140:141], v[108:109]
	v_pk_fma_f32 v[90:91], v[90:91], v[138:139], v[106:107]
	s_add_u32 s38, s28, s17
	v_readlane_b32 s17, v255, 27
	global_store_dwordx4 v[116:117], v[94:97], off
	global_store_dwordx4 v[116:117], v[90:93], off offset:64
	s_addc_u32 s39, s17, s39
	v_or_b32_e32 v102, 16, v98
	s_movk_i32 s15, 0x7fff
	s_waitcnt vmcnt(7)
	v_pk_fma_f32 v[76:77], v[84:85], v[144:145], v[120:121]
	v_pk_fma_f32 v[74:75], v[82:83], v[142:143], v[118:119]
	v_cndmask_b32_e32 v82, v0, v98, vcc
	v_mov_b32_e32 v0, s35
	v_mov_b32_e32 v84, s31
	v_cndmask_b32_e32 v83, 0, v99, vcc
	v_cndmask_b32_e32 v85, v0, v84, vcc
	v_mov_b32_e32 v0, s34
	v_mov_b32_e32 v84, s30
	v_cndmask_b32_e32 v84, v0, v84, vcc
	v_lshlrev_b64 v[82:83], 12, v[82:83]
	global_store_dwordx4 v[86:87], v[74:77], off
	s_waitcnt vmcnt(6)
	v_pk_fma_f32 v[72:73], v[72:73], v[136:137], v[128:129]
	v_pk_fma_f32 v[70:71], v[70:71], v[134:135], v[126:127]
	v_pk_fma_f32 v[76:77], v[80:81], v[140:141], v[124:125]
	v_pk_fma_f32 v[74:75], v[78:79], v[138:139], v[122:123]
	s_waitcnt vmcnt(5)
	v_pk_fma_f32 v[68:69], v[68:69], v[132:133], v[148:149]
	v_pk_fma_f32 v[66:67], v[66:67], v[130:131], v[146:147]
	v_lshl_add_u64 v[82:83], v[84:85], 0, v[82:83]
	global_store_dwordx4 v[86:87], v[74:77], off offset:64
	global_store_dwordx4 v[86:87], v[70:73], off offset:512
	global_store_dwordx4 v[86:87], v[66:69], off offset:576
	s_cmp_eq_u32 s100, 0
    	s_cbranch_scc1 .Lks6_cont
;     __device__ __forceinline__ void operator()(const f32x4 (&acc)[2][2][4][2], const Unit& u, int wr, int wc, int fr, int fq) const {
;     ...
;                 for (int mp = 0; mp < 2; ++mp) {
;                 f32x4 xv[2][2][2];
; #pragma unroll
;                 for (int mm = 0; mm < 2; ++mm) { const int gr = grb + (2 * mp + mm) * 16 + fr;
;                     const float* xr = (gr < MP ? xin_p + (size_t)gr * DM : xin_s + (size_t)(gr - MP) * DM) + col0;
; #pragma unroll
;                     for (int bj = 0; bj < 2; ++bj)
; #pragma unroll
;                         for (int n = 0; n < 2; ++n) xv[mm][bj][n] = *(const f32x4*)(xr + bj * HALF + n * 16); }
; #pragma unroll
;                 for (int mm = 0; mm < 2; ++mm) { const int m = 2 * mp + mm; const int gr = grb + m * 16 + fr; float* orow = out + (size_t)gr * DM + col0;
; #pragma unroll
;                     for (int bj = 0; bj < 2; ++bj)
; #pragma unroll
;                         for (int n = 0; n < 2; ++n) *(f32x4*)(orow + bj * HALF + n * 16) = xv[mm][bj][n] + gv[bj][n] * acc[ai][bj][m][n]; }
;                 }
    	s_waitcnt vmcnt(0)
    	s_andn2_b64 vcc, exec, s[4:5]
    	s_mov_b64 s[4:5], -1
    	s_branch .Lks6_end
    .Lks6_cont:
	v_lshl_add_u64 v[82:83], v[82:83], 0, v[180:181]
	v_cmp_lt_i32_e32 vcc, s15, v102
	v_lshl_add_u64 v[66:67], s[38:39], 0, v[180:181]
	global_load_dwordx4 v[78:81], v[66:67], off
	global_load_dwordx4 v[74:77], v[66:67], off offset:64
	global_load_dwordx4 v[70:73], v[66:67], off offset:512
	s_nop 0
	global_load_dwordx4 v[66:69], v[66:67], off offset:576
	s_nop 0
	global_load_dwordx4 v[94:97], v[82:83], off
	global_load_dwordx4 v[90:93], v[82:83], off offset:64
	global_load_dwordx4 v[86:89], v[82:83], off offset:512
	s_nop 0
	global_load_dwordx4 v[82:85], v[82:83], off offset:576
	s_and_saveexec_b64 s[38:39], vcc
	s_xor_b64 s[38:39], exec, s[38:39]
	v_add_u32_e32 v0, 0xffff8010, v98
	v_lshlrev_b64 v[100:101], 12, v[0:1]
	v_mov_b32_e32 v103, v1
	v_lshl_add_u64 v[104:105], s[34:35], 0, v[100:101]
	v_lshlrev_b64 v[100:101], 12, v[102:103]
	s_andn2_saveexec_b64 s[38:39], s[38:39]
	v_ashrrev_i32_e32 v103, 31, v102
	v_lshlrev_b64 v[100:101], 12, v[102:103]
	v_lshl_add_u64 v[104:105], s[30:31], 0, v[100:101]
	s_or_b64 exec, exec, s[38:39]
	v_lshl_add_u64 v[114:115], v[104:105], 0, v[180:181]
	global_load_dwordx4 v[102:105], v[114:115], off
	global_load_dwordx4 v[106:109], v[114:115], off offset:64
	global_load_dwordx4 v[110:113], v[114:115], off offset:512
	s_nop 0
	global_load_dwordx4 v[114:117], v[114:115], off offset:576
	v_lshlrev_b64 v[118:119], 12, v[98:99]
	s_waitcnt vmcnt(4)
	v_pk_fma_f32 v[82:83], v[50:51], v[66:67], v[82:83]
	v_or_b32_e32 v50, 32, v98
	s_mov_b32 s15, 0x8000
	v_pk_fma_f32 v[54:55], v[54:55], v[70:71], v[86:87]
	v_add_u32_e32 v0, 0xffff8020, v98
	v_lshl_add_u64 v[86:87], s[24:25], 0, v[118:119]
	v_ashrrev_i32_e32 v51, 31, v50
	v_cmp_gt_i32_e32 vcc, s15, v50
	v_pk_fma_f32 v[64:65], v[64:65], v[80:81], v[96:97]
	v_pk_fma_f32 v[62:63], v[62:63], v[78:79], v[94:95]
	v_pk_fma_f32 v[60:61], v[60:61], v[76:77], v[92:93]
	v_pk_fma_f32 v[58:59], v[58:59], v[74:75], v[90:91]
	v_pk_fma_f32 v[56:57], v[56:57], v[72:73], v[88:89]
	v_mov_b32_e32 v90, s35
	v_mov_b32_e32 v91, s31
	v_mov_b32_e32 v92, s34
	v_mov_b32_e32 v93, s30
	v_lshl_add_u64 v[86:87], v[86:87], 0, v[180:181]
	v_cndmask_b32_e32 v89, 0, v51, vcc
	v_cndmask_b32_e32 v88, v0, v50, vcc
	v_pk_fma_f32 v[84:85], v[52:53], v[68:69], v[84:85]
	v_lshl_add_u64 v[52:53], s[24:25], 0, v[100:101]
	v_cndmask_b32_e32 v91, v90, v91, vcc
	v_cndmask_b32_e32 v90, v92, v93, vcc
	global_store_dwordx4 v[86:87], v[62:65], off
	global_store_dwordx4 v[86:87], v[58:61], off offset:64
	global_store_dwordx4 v[86:87], v[54:57], off offset:512
	global_store_dwordx4 v[86:87], v[82:85], off offset:576
	v_lshl_add_u64 v[52:53], v[52:53], 0, v[180:181]
	v_lshlrev_b64 v[54:55], 12, v[88:89]
	v_lshl_add_u64 v[54:55], v[90:91], 0, v[54:55]
	v_lshl_add_u64 v[54:55], v[54:55], 0, v[180:181]
	s_movk_i32 s15, 0x7fff
	s_waitcnt vmcnt(7)
	v_pk_fma_f32 v[48:49], v[48:49], v[80:81], v[104:105]
	v_pk_fma_f32 v[46:47], v[46:47], v[78:79], v[102:103]
	s_waitcnt vmcnt(6)
	v_pk_fma_f32 v[44:45], v[44:45], v[76:77], v[108:109]
	v_pk_fma_f32 v[42:43], v[42:43], v[74:75], v[106:107]
	s_waitcnt vmcnt(5)
	v_pk_fma_f32 v[40:41], v[40:41], v[72:73], v[112:113]
	v_pk_fma_f32 v[38:39], v[38:39], v[70:71], v[110:111]
	s_waitcnt vmcnt(4)
	v_pk_fma_f32 v[36:37], v[36:37], v[68:69], v[116:117]
	v_pk_fma_f32 v[34:35], v[34:35], v[66:67], v[114:115]
	global_store_dwordx4 v[52:53], v[46:49], off
	global_store_dwordx4 v[52:53], v[42:45], off offset:64
	global_store_dwordx4 v[52:53], v[38:41], off offset:512
	global_store_dwordx4 v[52:53], v[34:37], off offset:576
	global_load_dwordx4 v[46:49], v[54:55], off
	s_nop 0
	global_load_dwordx4 v[42:45], v[54:55], off offset:64
	global_load_dwordx4 v[38:41], v[54:55], off offset:512
	global_load_dwordx4 v[34:37], v[54:55], off offset:576
	v_or_b32_e32 v54, 48, v98
	v_cmp_lt_i32_e32 vcc, s15, v54
	s_and_saveexec_b64 s[38:39], vcc
	s_xor_b64 s[38:39], exec, s[38:39]
	v_add_u32_e32 v0, 0xffff8030, v98
	v_lshlrev_b64 v[52:53], 12, v[0:1]
	v_mov_b32_e32 v55, v1
	v_lshl_add_u64 v[56:57], s[34:35], 0, v[52:53]
	v_lshlrev_b64 v[52:53], 12, v[54:55]
	s_andn2_saveexec_b64 s[38:39], s[38:39]
	v_ashrrev_i32_e32 v55, 31, v54
	v_lshlrev_b64 v[52:53], 12, v[54:55]
	v_lshl_add_u64 v[56:57], s[30:31], 0, v[52:53]
	s_or_b64 exec, exec, s[38:39]
	v_lshl_add_u64 v[82:83], v[56:57], 0, v[180:181]
	global_load_dwordx4 v[54:57], v[82:83], off
	global_load_dwordx4 v[58:61], v[82:83], off offset:64
	global_load_dwordx4 v[62:65], v[82:83], off offset:512
	s_nop 0
	global_load_dwordx4 v[82:85], v[82:83], off offset:576
	v_lshlrev_b64 v[50:51], 12, v[50:51]
	s_waitcnt vmcnt(4)
	v_pk_fma_f32 v[20:21], v[20:21], v[68:69], v[36:37]
	v_pk_fma_f32 v[18:19], v[18:19], v[66:67], v[34:35]
	v_lshl_add_u64 v[34:35], s[24:25], 0, v[52:53]
	v_lshl_add_u64 v[36:37], s[24:25], 0, v[50:51]
	v_pk_fma_f32 v[32:33], v[32:33], v[80:81], v[48:49]
	v_pk_fma_f32 v[30:31], v[30:31], v[78:79], v[46:47]
	v_lshl_add_u64 v[34:35], v[34:35], 0, v[180:181]
	v_lshl_add_u64 v[36:37], v[36:37], 0, v[180:181]
	s_andn2_b64 vcc, exec, s[4:5]
	s_mov_b64 s[4:5], -1
	v_pk_fma_f32 v[28:29], v[28:29], v[76:77], v[44:45]
	v_pk_fma_f32 v[26:27], v[26:27], v[74:75], v[42:43]
	v_pk_fma_f32 v[24:25], v[24:25], v[72:73], v[40:41]
	v_pk_fma_f32 v[22:23], v[22:23], v[70:71], v[38:39]
	global_store_dwordx4 v[36:37], v[30:33], off
	global_store_dwordx4 v[36:37], v[26:29], off offset:64
	global_store_dwordx4 v[36:37], v[22:25], off offset:512
	global_store_dwordx4 v[36:37], v[18:21], off offset:576
	s_waitcnt vmcnt(7)
	v_pk_fma_f32 v[16:17], v[16:17], v[80:81], v[56:57]
	v_pk_fma_f32 v[14:15], v[14:15], v[78:79], v[54:55]
	s_waitcnt vmcnt(6)
	v_pk_fma_f32 v[12:13], v[12:13], v[76:77], v[60:61]
	v_pk_fma_f32 v[10:11], v[10:11], v[74:75], v[58:59]
	s_waitcnt vmcnt(5)
	v_pk_fma_f32 v[8:9], v[8:9], v[72:73], v[64:65]
	v_pk_fma_f32 v[6:7], v[6:7], v[70:71], v[62:63]
	s_waitcnt vmcnt(4)
	v_pk_fma_f32 v[4:5], v[4:5], v[68:69], v[84:85]
	v_pk_fma_f32 v[2:3], v[2:3], v[66:67], v[82:83]
	global_store_dwordx4 v[34:35], v[14:17], off
	global_store_dwordx4 v[34:35], v[10:13], off offset:64
	global_store_dwordx4 v[34:35], v[6:9], off offset:512
	global_store_dwordx4 v[34:35], v[2:5], off offset:576
